# v015_norot
# speedup vs baseline: 1.0105x; 1.0105x over previous
; __device__ __forceinline__ void phase_mixers(const Params& p, int cidx, int layer) {
;     ...
; #pragma unroll 1
;   for (;;) {
;     const int tidx = opaque_tid();
;     const int wid = tidx >> 6;
;     __syncthreads();
;     if (tidx == 0) s_item = atomicAdd(ctr, 1);
;     __syncthreads();
;     const int it = s_item;
;     if (it >= N_SSM + N_POOL + N_ATT + n_cv) break;
;     if (it < N_SSM) ssm_item(p, layer, it & 127, tidx);
;     else if (it < N_SSM + N_POOL) pool_block_item(p, layer, (it - N_SSM) & 255, tidx);
;     else if (it < N_SSM + N_POOL + N_ATT) attn_wave_item(p, ((it - N_SSM - N_POOL) & 511) * 8 + wid, tidx);
;     else cv_item_B(p, (it - N_SSM - N_POOL - N_ATT) % CV_B, tidx);
.LBB0_77:
	s_or_b64 exec, exec, s[6:7]
	s_waitcnt lgkmcnt(0)
	s_barrier
	ds_read_b32 v0, v163 offset:20
	s_mov_b64 s[6:7], -1
	s_waitcnt lgkmcnt(0)
	v_cmp_le_i32_e32 vcc, s65, v0
	v_readfirstlane_b32 s64, v0
	s_cbranch_vccnz .LBB0_72
	v_ashrrev_i32_e32 v97, 6, v164
	s_cmpk_gt_i32 s64, 0x7f
	s_cbranch_scc0 .LBB0_197
	s_cmpk_gt_u32 s64, 0x17f
	s_cbranch_scc0 .LBB0_124
	s_cmpk_gt_u32 s64, 0x37f
	s_cbranch_scc0 .LBB0_115
	s_load_dwordx2 s[12:13], s[88:89], 0x80
	s_load_dwordx2 s[14:15], s[88:89], 0x68
	s_load_dwordx4 s[16:19], s[88:89], 0x10
	s_load_dwordx2 s[20:21], s[88:89], 0x98
	s_sub_u32 s6, s64, 0x380
	s_mov_b32 s27, 0
	s_waitcnt lgkmcnt(0)
	s_cmp_lt_u32 s6, 0x80
	s_cbranch_scc1 .Lcvm_wout0
	s_cmp_lt_u32 s6, 0x90
	s_cbranch_scc1 .Lcvm_glu0
	s_cmp_lt_u32 s6, 0x210
	s_cbranch_scc1 .Lcvm_win1
	s_cmp_lt_u32 s6, 0x290
	s_cbranch_scc1 .Lcvm_wout1
	s_cmp_lt_u32 s6, 0x2a0
	s_cbranch_scc1 .Lcvm_glu1
	s_sub_u32 s6, s6, 0x2a0
	s_lshl_b32 s28, s6, 18
	s_add_u32 s8, s18, s28
	s_addc_u32 s9, s19, 0
	s_add_u32 s8, s8, 0x100000
	s_addc_u32 s9, s9, 0
	s_lshl_b32 s28, s6, 17
	s_add_u32 s22, s20, s28
	s_addc_u32 s23, s21, 0
	s_add_u32 s22, s22, 0x10880000
	s_addc_u32 s23, s23, 0
	s_movk_i32 s24, 0x100
	s_movk_i32 s25, 0x100
	s_mov_b32 s26, 0
	s_mov_b32 s28, 0
	s_mov_b32 s29, 0
	s_branch .Lcvm_common
